# attention diet + scan address folding + simplified issue/wait flag logic in all ten GEMM k-loops (scalar compare + scc branch)
# baseline (speedup 1.0000x reference)
.LBB0_128:
	s_lshl_b32 s11, s7, 15
	v_or_b32_e32 v132, s11, v211
	v_add3_u32 v128, v132, s20, v212
	s_barrier
	ds_read_b128 v[172:175], v128
	ds_read_b128 v[168:171], v128 offset:1024
	ds_read_b128 v[164:167], v128 offset:2048
	ds_read_b128 v[160:163], v128 offset:3072
	ds_read_b128 v[156:159], v128 offset:4096
	ds_read_b128 v[152:155], v128 offset:5120
	ds_read_b128 v[140:143], v128 offset:6144
	ds_read_b128 v[128:131], v128 offset:7168
	v_add3_u32 v132, v132, s40, v212
	ds_read_b128 v[148:151], v132 offset:16384
	ds_read_b128 v[144:147], v132 offset:17408
	ds_read_b128 v[136:139], v132 offset:18432
	ds_read_b128 v[132:135], v132 offset:19456
	s_cmp_lt_u32 s10, 30
	s_cselect_b64 s[0:1], -1, 0
	s_or_b64 s[12:13], s[8:9], s[0:1]
	s_cbranch_scc1 .Lgk_i1
	s_waitcnt vmcnt(0)
	s_branch .LBB0_127
.Lgk_i1:
	v_lshl_add_u64 v[218:219], v[200:201], 0, s[2:3]
	v_lshl_add_u64 v[220:221], v[196:197], 0, s[2:3]
	s_addk_i32 s11, 0x8000
	v_cndmask_b32_e64 v219, v221, v219, s[0:1]
	v_cndmask_b32_e64 v218, v220, v218, s[0:1]
	v_lshl_add_u64 v[220:221], v[198:199], 0, s[2:3]
	v_lshl_add_u64 v[222:223], v[194:195], 0, s[2:3]
	s_cmp_gt_i32 s7, 0
	v_cndmask_b32_e64 v221, v223, v221, s[0:1]
	v_cndmask_b32_e64 v220, v222, v220, s[0:1]
	s_cselect_b32 s0, s11, 0x10000
	s_add_i32 s0, s15, s0
	s_add_i32 s12, s0, 0x4000
	s_mov_b32 m0, s0
	s_add_i32 s11, s0, 0x2000
	global_load_lds_dwordx4 v[220:221], off
	s_mov_b32 m0, s12
	s_add_i32 s1, s0, 0x6000
	v_lshl_add_u64 v[224:225], v[220:221], 0, s[94:95]
	global_load_lds_dwordx4 v[218:219], off
	s_mov_b32 m0, s11
	v_lshl_add_u64 v[222:223], v[218:219], 0, s[94:95]
	global_load_lds_dwordx4 v[224:225], off
	s_mov_b32 m0, s1
	s_nop 0
	global_load_lds_dwordx4 v[222:223], off
	s_waitcnt vmcnt(4)
	s_branch .LBB0_127

.LBB0_136:
	s_lshl_b32 s10, s52, 15
	v_or_b32_e32 v128, s10, v211
	v_add_u32_e32 v132, v128, v212
	ds_read_b128 v[172:175], v132
	ds_read_b128 v[168:171], v132 offset:1024
	ds_read_b128 v[164:167], v132 offset:2048
	ds_read_b128 v[160:163], v132 offset:3072
	ds_read_b128 v[156:159], v132 offset:4096
	ds_read_b128 v[152:155], v132 offset:5120
	ds_read_b128 v[136:139], v132 offset:6144
	ds_read_b128 v[128:131], v132 offset:7168
	v_add_u32_e32 v132, s41, v132
	ds_read_b128 v[144:147], v132 offset:16384
	ds_read_b128 v[148:151], v132 offset:17408
	ds_read_b128 v[140:143], v132 offset:18432
	ds_read_b128 v[132:135], v132 offset:19456
	s_cmp_lt_u32 s7, 30
	s_cselect_b64 s[0:1], -1, 0
	s_nor_b64 s[12:13], s[8:9], s[0:1]
	s_cbranch_scc1 .LBB0_138
	v_lshl_add_u64 v[194:195], v[186:187], 0, s[2:3]
	v_lshl_add_u64 v[196:197], v[190:191], 0, s[2:3]
	s_addk_i32 s10, 0x8000
	v_cndmask_b32_e64 v195, v197, v195, s[0:1]
	v_cndmask_b32_e64 v194, v196, v194, s[0:1]
	v_lshl_add_u64 v[196:197], v[188:189], 0, s[2:3]
	v_lshl_add_u64 v[198:199], v[192:193], 0, s[2:3]
	s_cmp_gt_i32 s52, 0
	v_cndmask_b32_e64 v197, v199, v197, s[0:1]
	v_cndmask_b32_e64 v196, v198, v196, s[0:1]
	s_cselect_b32 s0, s10, 0x10000
	s_add_i32 s0, s15, s0
	s_add_i32 s11, s0, 0x4000
	s_mov_b32 m0, s0
	s_add_i32 s10, s0, 0x2000
	global_load_lds_dwordx4 v[196:197], off
	s_mov_b32 m0, s11
	s_add_i32 s1, s0, 0x6000
	v_lshl_add_u64 v[200:201], v[196:197], 0, s[94:95]
	global_load_lds_dwordx4 v[194:195], off
	s_mov_b32 m0, s10
	v_lshl_add_u64 v[198:199], v[194:195], 0, s[94:95]
	global_load_lds_dwordx4 v[200:201], off
	s_mov_b32 m0, s1
	s_nop 0
	global_load_lds_dwordx4 v[198:199], off
.LBB0_138:
	s_waitcnt lgkmcnt(0)
	v_mfma_f32_16x16x32_bf16 v[124:127], v[144:147], v[172:175], v[124:127]
	s_waitcnt lgkmcnt(0)
	v_mfma_f32_16x16x32_bf16 v[120:123], v[148:151], v[172:175], v[120:123]
	s_barrier
	v_mfma_f32_16x16x32_bf16 v[116:119], v[140:143], v[172:175], v[116:119]
	v_mfma_f32_16x16x32_bf16 v[112:115], v[132:135], v[172:175], v[112:115]
	v_mfma_f32_16x16x32_bf16 v[108:111], v[144:147], v[168:171], v[108:111]
	v_mfma_f32_16x16x32_bf16 v[104:107], v[148:151], v[168:171], v[104:107]
	v_mfma_f32_16x16x32_bf16 v[100:103], v[140:143], v[168:171], v[100:103]
	v_mfma_f32_16x16x32_bf16 v[96:99], v[132:135], v[168:171], v[96:99]
	v_mfma_f32_16x16x32_bf16 v[92:95], v[144:147], v[164:167], v[92:95]
	v_mfma_f32_16x16x32_bf16 v[88:91], v[148:151], v[164:167], v[88:91]
	v_mfma_f32_16x16x32_bf16 v[84:87], v[140:143], v[164:167], v[84:87]
	v_mfma_f32_16x16x32_bf16 v[80:83], v[132:135], v[164:167], v[80:83]
	v_mfma_f32_16x16x32_bf16 v[76:79], v[144:147], v[160:163], v[76:79]
	v_mfma_f32_16x16x32_bf16 v[72:75], v[148:151], v[160:163], v[72:75]
	v_mfma_f32_16x16x32_bf16 v[68:71], v[140:143], v[160:163], v[68:71]
	v_mfma_f32_16x16x32_bf16 v[64:67], v[132:135], v[160:163], v[64:67]
	v_mfma_f32_16x16x32_bf16 v[60:63], v[144:147], v[156:159], v[60:63]
	v_mfma_f32_16x16x32_bf16 v[56:59], v[148:151], v[156:159], v[56:59]
	v_mfma_f32_16x16x32_bf16 v[52:55], v[140:143], v[156:159], v[52:55]
	v_mfma_f32_16x16x32_bf16 v[48:51], v[132:135], v[156:159], v[48:51]
	v_mfma_f32_16x16x32_bf16 v[44:47], v[144:147], v[152:155], v[44:47]
	v_mfma_f32_16x16x32_bf16 v[40:43], v[148:151], v[152:155], v[40:43]
	v_mfma_f32_16x16x32_bf16 v[36:39], v[140:143], v[152:155], v[36:39]
	v_mfma_f32_16x16x32_bf16 v[32:35], v[132:135], v[152:155], v[32:35]
	v_mfma_f32_16x16x32_bf16 v[28:31], v[144:147], v[136:139], v[28:31]
	v_mfma_f32_16x16x32_bf16 v[24:27], v[148:151], v[136:139], v[24:27]
	v_mfma_f32_16x16x32_bf16 v[20:23], v[140:143], v[136:139], v[20:23]
	v_mfma_f32_16x16x32_bf16 v[16:19], v[132:135], v[136:139], v[16:19]
	v_mfma_f32_16x16x32_bf16 v[12:15], v[144:147], v[128:131], v[12:15]
	v_mfma_f32_16x16x32_bf16 v[8:11], v[148:151], v[128:131], v[8:11]
	v_mfma_f32_16x16x32_bf16 v[4:7], v[140:143], v[128:131], v[4:7]
	v_mfma_f32_16x16x32_bf16 v[0:3], v[132:135], v[128:131], v[0:3]
	s_cmp_lg_u64 s[12:13], 0
	s_cbranch_scc1 .Lgk_w1
	s_waitcnt vmcnt(4)
	s_branch .LBB0_135
.Lgk_w1:
	s_waitcnt vmcnt(0)
	s_branch .LBB0_135

.LBB0_542:
	s_mul_i32 s26, s6, 0xc000
	v_or_b32_e32 v64, s26, v153
	v_add_u32_e32 v65, v64, v152
	v_add_u32_e32 v64, v64, v154
	s_barrier
	ds_read_b128 v[124:127], v65
	ds_read_b128 v[116:119], v65 offset:2048
	ds_read_b128 v[84:87], v64 offset:32768
	ds_read_b128 v[88:91], v64 offset:34816
	ds_read_b128 v[104:107], v65 offset:4096
	ds_read_b128 v[92:95], v65 offset:6144
	ds_read_b128 v[108:111], v64 offset:36864
	ds_read_b128 v[112:115], v64 offset:38912
	v_or_b32_e32 v64, s26, v155
	v_add_u32_e32 v65, v64, v152
	v_add_u32_e32 v68, v64, v154
	ds_read_b128 v[120:123], v65
	ds_read_b128 v[100:103], v65 offset:2048
	ds_read_b128 v[80:83], v68 offset:32768
	ds_read_b128 v[76:79], v68 offset:34816
	ds_read_b128 v[96:99], v65 offset:4096
	ds_read_b128 v[64:67], v65 offset:6144
	ds_read_b128 v[72:75], v68 offset:36864
	ds_read_b128 v[68:71], v68 offset:38912
	s_cmp_lt_u32 s24, 30
	s_cselect_b64 s[0:1], -1, 0
	s_or_b64 s[12:13], s[2:3], s[0:1]
	s_cbranch_scc1 .Lgk_i2
	s_waitcnt vmcnt(0)
	s_branch .LBB0_541
.Lgk_i2:
	v_lshl_add_u64 v[160:161], v[150:151], 0, s[8:9]
	v_lshl_add_u64 v[162:163], v[146:147], 0, s[8:9]
	s_add_i32 s26, s26, 0xffff4000
	v_cndmask_b32_e64 v161, v163, v161, s[0:1]
	v_cndmask_b32_e64 v160, v162, v160, s[0:1]
	v_lshl_add_u64 v[162:163], v[148:149], 0, s[8:9]
	v_lshl_add_u64 v[164:165], v[144:145], 0, s[8:9]
	s_cmp_gt_i32 s6, 0
	v_cndmask_b32_e64 v163, v165, v163, s[0:1]
	v_cndmask_b32_e64 v162, v164, v162, s[0:1]
	s_cselect_b32 s0, s26, 0x18000
	s_add_i32 s0, s15, s0
	s_mov_b32 m0, s0
	v_lshl_add_u64 v[164:165], v[162:163], 0, s[94:95]
	global_load_lds_dwordx4 v[162:163], off
	s_add_i32 m0, s0, 0x2000
	s_nop 0
	global_load_lds_dwordx4 v[164:165], off
	v_lshl_add_u64 v[164:165], v[162:163], 0, s[36:37]
	s_add_i32 m0, s0, 0x4000
	v_lshl_add_u64 v[162:163], v[162:163], 0, s[4:5]
	global_load_lds_dwordx4 v[164:165], off
	s_add_i32 m0, s0, 0x6000
	s_nop 0
	global_load_lds_dwordx4 v[162:163], off
	s_add_i32 m0, s0, 0x8000
	s_nop 0
	global_load_lds_dwordx4 v[160:161], off
	v_lshl_add_u64 v[160:161], v[160:161], 0, s[94:95]
	s_add_i32 m0, s0, 0xa000
	s_nop 0
	global_load_lds_dwordx4 v[160:161], off
	s_waitcnt vmcnt(6)
	s_branch .LBB0_541

.LBB0_550:
	s_mul_i32 s24, s11, 0xc000
	v_or_b32_e32 v64, s24, v153
	v_add_u32_e32 v65, v64, v152
	v_add_u32_e32 v64, v64, v154
	ds_read_b128 v[124:127], v65
	ds_read_b128 v[116:119], v65 offset:2048
	ds_read_b128 v[80:83], v64 offset:32768
	ds_read_b128 v[84:87], v64 offset:34816
	ds_read_b128 v[104:107], v65 offset:4096
	ds_read_b128 v[92:95], v65 offset:6144
	ds_read_b128 v[108:111], v64 offset:36864
	ds_read_b128 v[112:115], v64 offset:38912
	v_or_b32_e32 v64, s24, v155
	v_add_u32_e32 v65, v64, v152
	v_add_u32_e32 v68, v64, v154
	ds_read_b128 v[120:123], v65
	ds_read_b128 v[100:103], v65 offset:2048
	ds_read_b128 v[72:75], v68 offset:32768
	ds_read_b128 v[76:79], v68 offset:34816
	ds_read_b128 v[96:99], v65 offset:4096
	ds_read_b128 v[64:67], v65 offset:6144
	ds_read_b128 v[88:91], v68 offset:36864
	ds_read_b128 v[68:71], v68 offset:38912
	s_cmp_lt_u32 s6, 30
	s_cselect_b64 s[0:1], -1, 0
	s_nor_b64 s[12:13], s[2:3], s[0:1]
	s_cbranch_scc1 .LBB0_552
	v_lshl_add_u64 v[144:145], v[136:137], 0, s[8:9]
	v_lshl_add_u64 v[146:147], v[140:141], 0, s[8:9]
	s_add_i32 s24, s24, 0xffff4000
	v_cndmask_b32_e64 v145, v147, v145, s[0:1]
	v_cndmask_b32_e64 v144, v146, v144, s[0:1]
	v_lshl_add_u64 v[146:147], v[138:139], 0, s[8:9]
	v_lshl_add_u64 v[148:149], v[142:143], 0, s[8:9]
	s_cmp_gt_i32 s11, 0
	v_cndmask_b32_e64 v147, v149, v147, s[0:1]
	v_cndmask_b32_e64 v146, v148, v146, s[0:1]
	s_cselect_b32 s0, s24, 0x18000
	s_add_i32 s0, s15, s0
	s_mov_b32 m0, s0
	v_lshl_add_u64 v[148:149], v[146:147], 0, s[94:95]
	global_load_lds_dwordx4 v[146:147], off
	s_add_i32 m0, s0, 0x2000
	s_nop 0
	global_load_lds_dwordx4 v[148:149], off
	v_lshl_add_u64 v[148:149], v[146:147], 0, s[36:37]
	s_add_i32 m0, s0, 0x4000
	v_lshl_add_u64 v[146:147], v[146:147], 0, s[4:5]
	global_load_lds_dwordx4 v[148:149], off
	s_add_i32 m0, s0, 0x6000
	s_nop 0
	global_load_lds_dwordx4 v[146:147], off
	s_add_i32 m0, s0, 0x8000
	s_nop 0
	global_load_lds_dwordx4 v[144:145], off
	v_lshl_add_u64 v[144:145], v[144:145], 0, s[94:95]
	s_add_i32 m0, s0, 0xa000
	s_nop 0
	global_load_lds_dwordx4 v[144:145], off
.LBB0_552:
	s_waitcnt lgkmcnt(0)
	v_mfma_f32_16x16x32_bf16 v[60:63], v[80:83], v[124:127], v[60:63]
	s_waitcnt lgkmcnt(0)
	v_mfma_f32_16x16x32_bf16 v[56:59], v[84:87], v[124:127], v[56:59]
	s_barrier
	v_mfma_f32_16x16x32_bf16 v[52:55], v[108:111], v[124:127], v[52:55]
	v_mfma_f32_16x16x32_bf16 v[48:51], v[112:115], v[124:127], v[48:51]
	v_mfma_f32_16x16x32_bf16 v[44:47], v[80:83], v[116:119], v[44:47]
	v_mfma_f32_16x16x32_bf16 v[40:43], v[84:87], v[116:119], v[40:43]
	v_mfma_f32_16x16x32_bf16 v[36:39], v[108:111], v[116:119], v[36:39]
	v_mfma_f32_16x16x32_bf16 v[32:35], v[112:115], v[116:119], v[32:35]
	v_mfma_f32_16x16x32_bf16 v[28:31], v[80:83], v[104:107], v[28:31]
	v_mfma_f32_16x16x32_bf16 v[24:27], v[84:87], v[104:107], v[24:27]
	v_mfma_f32_16x16x32_bf16 v[20:23], v[108:111], v[104:107], v[20:23]
	v_mfma_f32_16x16x32_bf16 v[16:19], v[112:115], v[104:107], v[16:19]
	v_mfma_f32_16x16x32_bf16 v[12:15], v[80:83], v[92:95], v[12:15]
	v_mfma_f32_16x16x32_bf16 v[8:11], v[84:87], v[92:95], v[8:11]
	v_mfma_f32_16x16x32_bf16 v[0:3], v[108:111], v[92:95], v[0:3]
	v_mfma_f32_16x16x32_bf16 v[4:7], v[112:115], v[92:95], v[4:7]
	v_mfma_f32_16x16x32_bf16 v[60:63], v[72:75], v[120:123], v[60:63]
	v_mfma_f32_16x16x32_bf16 v[56:59], v[76:79], v[120:123], v[56:59]
	v_mfma_f32_16x16x32_bf16 v[52:55], v[88:91], v[120:123], v[52:55]
	v_mfma_f32_16x16x32_bf16 v[48:51], v[68:71], v[120:123], v[48:51]
	v_mfma_f32_16x16x32_bf16 v[44:47], v[72:75], v[100:103], v[44:47]
	v_mfma_f32_16x16x32_bf16 v[40:43], v[76:79], v[100:103], v[40:43]
	v_mfma_f32_16x16x32_bf16 v[36:39], v[88:91], v[100:103], v[36:39]
	v_mfma_f32_16x16x32_bf16 v[32:35], v[68:71], v[100:103], v[32:35]
	v_mfma_f32_16x16x32_bf16 v[28:31], v[72:75], v[96:99], v[28:31]
	v_mfma_f32_16x16x32_bf16 v[24:27], v[76:79], v[96:99], v[24:27]
	v_mfma_f32_16x16x32_bf16 v[20:23], v[88:91], v[96:99], v[20:23]
	v_mfma_f32_16x16x32_bf16 v[16:19], v[68:71], v[96:99], v[16:19]
	v_mfma_f32_16x16x32_bf16 v[12:15], v[72:75], v[64:67], v[12:15]
	v_mfma_f32_16x16x32_bf16 v[8:11], v[76:79], v[64:67], v[8:11]
	v_mfma_f32_16x16x32_bf16 v[0:3], v[88:91], v[64:67], v[0:3]
	v_mfma_f32_16x16x32_bf16 v[4:7], v[68:71], v[64:67], v[4:7]
	s_cmp_lg_u64 s[12:13], 0
	s_cbranch_scc1 .Lgk_w2
	s_waitcnt vmcnt(6)
	s_branch .LBB0_549

.LBB0_702:
	s_lshl_b32 s54, s64, 15
	v_or_b32_e32 v132, s54, v202
	v_add3_u32 v128, v132, s33, v203
	s_barrier
	ds_read_b128 v[172:175], v128
	ds_read_b128 v[168:171], v128 offset:1024
	ds_read_b128 v[164:167], v128 offset:2048
	ds_read_b128 v[160:163], v128 offset:3072
	ds_read_b128 v[156:159], v128 offset:4096
	ds_read_b128 v[152:155], v128 offset:5120
	ds_read_b128 v[140:143], v128 offset:6144
	ds_read_b128 v[128:131], v128 offset:7168
	v_add3_u32 v132, v132, s34, v203
	ds_read_b128 v[148:151], v132 offset:16384
	ds_read_b128 v[144:147], v132 offset:17408
	ds_read_b128 v[136:139], v132 offset:18432
	ds_read_b128 v[132:135], v132 offset:19456
	s_cmp_lt_u32 s39, 30
	s_cselect_b64 s[2:3], -1, 0
	s_or_b64 s[12:13], s[16:17], s[2:3]
	s_cbranch_scc1 .Lgk_i3
	s_waitcnt vmcnt(0)
	s_branch .LBB0_701
.Lgk_i3:
	v_lshl_add_u64 v[194:195], v[192:193], 0, s[8:9]
	v_lshl_add_u64 v[196:197], v[188:189], 0, s[8:9]
	s_addk_i32 s54, 0x8000
	v_cndmask_b32_e64 v195, v197, v195, s[2:3]
	v_cndmask_b32_e64 v194, v196, v194, s[2:3]
	v_lshl_add_u64 v[196:197], v[190:191], 0, s[8:9]
	v_lshl_add_u64 v[198:199], v[186:187], 0, s[8:9]
	s_cmp_gt_i32 s64, 0
	v_cndmask_b32_e64 v197, v199, v197, s[2:3]
	v_cndmask_b32_e64 v196, v198, v196, s[2:3]
	s_cselect_b32 s2, s54, 0x10000
	s_add_i32 s2, s35, s2
	s_add_i32 s13, s2, 0x4000
	s_mov_b32 m0, s2
	s_add_i32 s12, s2, 0x2000
	global_load_lds_dwordx4 v[196:197], off
	s_mov_b32 m0, s13
	s_add_i32 s3, s2, 0x6000
	v_lshl_add_u64 v[200:201], v[196:197], 0, s[72:73]
	global_load_lds_dwordx4 v[194:195], off
	s_mov_b32 m0, s12
	v_lshl_add_u64 v[198:199], v[194:195], 0, s[72:73]
	global_load_lds_dwordx4 v[200:201], off
	s_mov_b32 m0, s3
	s_nop 0
	global_load_lds_dwordx4 v[198:199], off
	s_waitcnt vmcnt(4)
	s_branch .LBB0_701

.LBB0_710:
	s_lshl_b32 s54, s64, 15
	v_or_b32_e32 v128, s54, v202
	v_add_u32_e32 v132, v128, v203
	ds_read_b128 v[172:175], v132
	ds_read_b128 v[168:171], v132 offset:1024
	ds_read_b128 v[164:167], v132 offset:2048
	ds_read_b128 v[160:163], v132 offset:3072
	ds_read_b128 v[156:159], v132 offset:4096
	ds_read_b128 v[152:155], v132 offset:5120
	ds_read_b128 v[136:139], v132 offset:6144
	ds_read_b128 v[128:131], v132 offset:7168
	v_add_u32_e32 v132, s36, v132
	ds_read_b128 v[144:147], v132 offset:16384
	ds_read_b128 v[148:151], v132 offset:17408
	ds_read_b128 v[140:143], v132 offset:18432
	ds_read_b128 v[132:135], v132 offset:19456
	s_cmp_lt_u32 s39, 30
	s_cselect_b64 s[2:3], -1, 0
	s_nor_b64 s[12:13], s[16:17], s[2:3]
	s_cbranch_scc1 .LBB0_712
	v_lshl_add_u64 v[194:195], v[192:193], 0, s[8:9]
	v_lshl_add_u64 v[196:197], v[188:189], 0, s[8:9]
	s_addk_i32 s54, 0x8000
	v_cndmask_b32_e64 v195, v197, v195, s[2:3]
	v_cndmask_b32_e64 v194, v196, v194, s[2:3]
	v_lshl_add_u64 v[196:197], v[190:191], 0, s[8:9]
	v_lshl_add_u64 v[198:199], v[186:187], 0, s[8:9]
	s_cmp_gt_i32 s64, 0
	v_cndmask_b32_e64 v197, v199, v197, s[2:3]
	v_cndmask_b32_e64 v196, v198, v196, s[2:3]
	s_cselect_b32 s2, s54, 0x10000
	s_add_i32 s2, s35, s2
	s_add_i32 s55, s2, 0x4000
	s_mov_b32 m0, s2
	s_add_i32 s54, s2, 0x2000
	global_load_lds_dwordx4 v[196:197], off
	s_mov_b32 m0, s55
	s_add_i32 s3, s2, 0x6000
	v_lshl_add_u64 v[200:201], v[196:197], 0, s[72:73]
	global_load_lds_dwordx4 v[194:195], off
	s_mov_b32 m0, s54
	v_lshl_add_u64 v[198:199], v[194:195], 0, s[72:73]
	global_load_lds_dwordx4 v[200:201], off
	s_mov_b32 m0, s3
	s_nop 0
	global_load_lds_dwordx4 v[198:199], off

.LBB0_721:
	s_lshl_b32 s13, s64, 15
	v_or_b32_e32 v132, s13, v202
	v_add3_u32 v128, v132, s33, v203
	s_barrier
	ds_read_b128 v[172:175], v128
	ds_read_b128 v[168:171], v128 offset:1024
	ds_read_b128 v[164:167], v128 offset:2048
	ds_read_b128 v[160:163], v128 offset:3072
	ds_read_b128 v[156:159], v128 offset:4096
	ds_read_b128 v[152:155], v128 offset:5120
	ds_read_b128 v[140:143], v128 offset:6144
	ds_read_b128 v[128:131], v128 offset:7168
	v_add3_u32 v132, v132, s34, v203
	ds_read_b128 v[148:151], v132 offset:16384
	ds_read_b128 v[144:147], v132 offset:17408
	ds_read_b128 v[136:139], v132 offset:18432
	ds_read_b128 v[132:135], v132 offset:19456
	s_cmp_lt_u32 s12, 30
	s_cselect_b64 s[0:1], -1, 0
	s_or_b64 s[8:9], s[16:17], s[0:1]
	s_cbranch_scc1 .Lgk_i4
	s_waitcnt vmcnt(0)
	s_branch .LBB0_720
.Lgk_i4:
	v_lshl_add_u64 v[210:211], v[200:201], 0, s[2:3]
	v_lshl_add_u64 v[212:213], v[196:197], 0, s[2:3]
	s_addk_i32 s13, 0x8000
	v_cndmask_b32_e64 v211, v213, v211, s[0:1]
	v_cndmask_b32_e64 v210, v212, v210, s[0:1]
	v_lshl_add_u64 v[212:213], v[198:199], 0, s[2:3]
	v_lshl_add_u64 v[214:215], v[194:195], 0, s[2:3]
	s_cmp_gt_i32 s64, 0
	v_cndmask_b32_e64 v213, v215, v213, s[0:1]
	v_cndmask_b32_e64 v212, v214, v212, s[0:1]
	s_cselect_b32 s0, s13, 0x10000
	s_add_i32 s0, s35, s0
	s_add_i32 s9, s0, 0x4000
	s_mov_b32 m0, s0
	s_add_i32 s8, s0, 0x2000
	global_load_lds_dwordx4 v[212:213], off
	s_mov_b32 m0, s9
	s_add_i32 s1, s0, 0x6000
	v_lshl_add_u64 v[216:217], v[212:213], 0, s[72:73]
	global_load_lds_dwordx4 v[210:211], off
	s_mov_b32 m0, s8
	v_lshl_add_u64 v[214:215], v[210:211], 0, s[72:73]
	global_load_lds_dwordx4 v[216:217], off
	s_mov_b32 m0, s1
	s_nop 0
	global_load_lds_dwordx4 v[214:215], off
	s_waitcnt vmcnt(4)
	s_branch .LBB0_720

.LBB0_729:
	s_lshl_b32 s13, s38, 15
	v_or_b32_e32 v128, s13, v202
	v_add_u32_e32 v132, v128, v203
	ds_read_b128 v[172:175], v132
	ds_read_b128 v[168:171], v132 offset:1024
	ds_read_b128 v[164:167], v132 offset:2048
	ds_read_b128 v[160:163], v132 offset:3072
	ds_read_b128 v[156:159], v132 offset:4096
	ds_read_b128 v[152:155], v132 offset:5120
	ds_read_b128 v[136:139], v132 offset:6144
	ds_read_b128 v[128:131], v132 offset:7168
	v_add_u32_e32 v132, s36, v132
	ds_read_b128 v[144:147], v132 offset:16384
	ds_read_b128 v[148:151], v132 offset:17408
	ds_read_b128 v[140:143], v132 offset:18432
	ds_read_b128 v[132:135], v132 offset:19456
	s_cmp_lt_u32 s12, 30
	s_cselect_b64 s[0:1], -1, 0
	s_nor_b64 s[8:9], s[16:17], s[0:1]
	s_cbranch_scc1 .LBB0_731
	v_lshl_add_u64 v[194:195], v[186:187], 0, s[2:3]
	v_lshl_add_u64 v[196:197], v[190:191], 0, s[2:3]
	s_addk_i32 s13, 0x8000
	v_cndmask_b32_e64 v195, v197, v195, s[0:1]
	v_cndmask_b32_e64 v194, v196, v194, s[0:1]
	v_lshl_add_u64 v[196:197], v[188:189], 0, s[2:3]
	v_lshl_add_u64 v[198:199], v[192:193], 0, s[2:3]
	s_cmp_gt_i32 s38, 0
	v_cndmask_b32_e64 v197, v199, v197, s[0:1]
	v_cndmask_b32_e64 v196, v198, v196, s[0:1]
	s_cselect_b32 s0, s13, 0x10000
	s_add_i32 s0, s35, s0
	s_add_i32 s39, s0, 0x4000
	s_mov_b32 m0, s0
	s_add_i32 s13, s0, 0x2000
	global_load_lds_dwordx4 v[196:197], off
	s_mov_b32 m0, s39
	s_add_i32 s1, s0, 0x6000
	v_lshl_add_u64 v[200:201], v[196:197], 0, s[72:73]
	global_load_lds_dwordx4 v[194:195], off
	s_mov_b32 m0, s13
	v_lshl_add_u64 v[198:199], v[194:195], 0, s[72:73]
	global_load_lds_dwordx4 v[200:201], off
	s_mov_b32 m0, s1
	s_nop 0
	global_load_lds_dwordx4 v[198:199], off
.LBB0_731:
	s_waitcnt lgkmcnt(0)
	v_mfma_f32_16x16x32_bf16 v[124:127], v[172:175], v[144:147], v[124:127]
	s_waitcnt lgkmcnt(0)
	v_mfma_f32_16x16x32_bf16 v[120:123], v[172:175], v[148:151], v[120:123]
	s_barrier
	v_mfma_f32_16x16x32_bf16 v[116:119], v[172:175], v[140:143], v[116:119]
	v_mfma_f32_16x16x32_bf16 v[112:115], v[172:175], v[132:135], v[112:115]
	v_mfma_f32_16x16x32_bf16 v[108:111], v[168:171], v[144:147], v[108:111]
	v_mfma_f32_16x16x32_bf16 v[104:107], v[168:171], v[148:151], v[104:107]
	v_mfma_f32_16x16x32_bf16 v[100:103], v[168:171], v[140:143], v[100:103]
	v_mfma_f32_16x16x32_bf16 v[96:99], v[168:171], v[132:135], v[96:99]
	v_mfma_f32_16x16x32_bf16 v[92:95], v[164:167], v[144:147], v[92:95]
	v_mfma_f32_16x16x32_bf16 v[88:91], v[164:167], v[148:151], v[88:91]
	v_mfma_f32_16x16x32_bf16 v[84:87], v[164:167], v[140:143], v[84:87]
	v_mfma_f32_16x16x32_bf16 v[80:83], v[164:167], v[132:135], v[80:83]
	v_mfma_f32_16x16x32_bf16 v[76:79], v[160:163], v[144:147], v[76:79]
	v_mfma_f32_16x16x32_bf16 v[72:75], v[160:163], v[148:151], v[72:75]
	v_mfma_f32_16x16x32_bf16 v[68:71], v[160:163], v[140:143], v[68:71]
	v_mfma_f32_16x16x32_bf16 v[64:67], v[160:163], v[132:135], v[64:67]
	v_mfma_f32_16x16x32_bf16 v[60:63], v[156:159], v[144:147], v[60:63]
	v_mfma_f32_16x16x32_bf16 v[56:59], v[156:159], v[148:151], v[56:59]
	v_mfma_f32_16x16x32_bf16 v[52:55], v[156:159], v[140:143], v[52:55]
	v_mfma_f32_16x16x32_bf16 v[48:51], v[156:159], v[132:135], v[48:51]
	v_mfma_f32_16x16x32_bf16 v[44:47], v[152:155], v[144:147], v[44:47]
	v_mfma_f32_16x16x32_bf16 v[40:43], v[152:155], v[148:151], v[40:43]
	v_mfma_f32_16x16x32_bf16 v[36:39], v[152:155], v[140:143], v[36:39]
	v_mfma_f32_16x16x32_bf16 v[32:35], v[152:155], v[132:135], v[32:35]
	v_mfma_f32_16x16x32_bf16 v[28:31], v[136:139], v[144:147], v[28:31]
	v_mfma_f32_16x16x32_bf16 v[24:27], v[136:139], v[148:151], v[24:27]
	v_mfma_f32_16x16x32_bf16 v[20:23], v[136:139], v[140:143], v[20:23]
	v_mfma_f32_16x16x32_bf16 v[16:19], v[136:139], v[132:135], v[16:19]
	v_mfma_f32_16x16x32_bf16 v[12:15], v[128:131], v[144:147], v[12:15]
	v_mfma_f32_16x16x32_bf16 v[8:11], v[128:131], v[148:151], v[8:11]
	v_mfma_f32_16x16x32_bf16 v[4:7], v[128:131], v[140:143], v[4:7]
	v_mfma_f32_16x16x32_bf16 v[0:3], v[128:131], v[132:135], v[0:3]
	s_cmp_lg_u64 s[8:9], 0
	s_cbranch_scc1 .Lgk_w4
	s_waitcnt vmcnt(4)
	s_branch .LBB0_728

.LBB0_1221:
	s_mul_i32 s54, s38, 0xc000
	v_or_b32_e32 v64, s54, v153
	v_add_u32_e32 v65, v64, v152
	v_add_u32_e32 v64, v64, v154
	s_barrier
	ds_read_b128 v[124:127], v65
	ds_read_b128 v[116:119], v65 offset:2048
	ds_read_b128 v[84:87], v64 offset:32768
	ds_read_b128 v[88:91], v64 offset:34816
	ds_read_b128 v[104:107], v65 offset:4096
	ds_read_b128 v[92:95], v65 offset:6144
	ds_read_b128 v[108:111], v64 offset:36864
	ds_read_b128 v[112:115], v64 offset:38912
	v_or_b32_e32 v64, s54, v155
	v_add_u32_e32 v65, v64, v152
	v_add_u32_e32 v68, v64, v154
	ds_read_b128 v[120:123], v65
	ds_read_b128 v[100:103], v65 offset:2048
	ds_read_b128 v[80:83], v68 offset:32768
	ds_read_b128 v[76:79], v68 offset:34816
	ds_read_b128 v[96:99], v65 offset:4096
	ds_read_b128 v[64:67], v65 offset:6144
	ds_read_b128 v[72:75], v68 offset:36864
	ds_read_b128 v[68:71], v68 offset:38912
	s_cmp_lt_u32 s56, 30
	s_cselect_b64 s[0:1], -1, 0
	s_or_b64 s[14:15], s[8:9], s[0:1]
	s_cbranch_scc1 .Lgk_i5
	s_waitcnt vmcnt(0)
	s_branch .LBB0_1220
.Lgk_i5:
	v_lshl_add_u64 v[160:161], v[150:151], 0, s[12:13]
	v_lshl_add_u64 v[162:163], v[146:147], 0, s[12:13]
	s_add_i32 s54, s54, 0xffff4000
	v_cndmask_b32_e64 v161, v163, v161, s[0:1]
	v_cndmask_b32_e64 v160, v162, v160, s[0:1]
	v_lshl_add_u64 v[162:163], v[148:149], 0, s[12:13]
	v_lshl_add_u64 v[164:165], v[144:145], 0, s[12:13]
	s_cmp_gt_i32 s38, 0
	v_cndmask_b32_e64 v163, v165, v163, s[0:1]
	v_cndmask_b32_e64 v162, v164, v162, s[0:1]
	s_cselect_b32 s0, s54, 0x18000
	s_add_i32 s0, s19, s0
	s_mov_b32 m0, s0
	v_lshl_add_u64 v[164:165], v[162:163], 0, s[72:73]
	global_load_lds_dwordx4 v[162:163], off
	s_add_i32 m0, s0, 0x2000
	s_nop 0
	global_load_lds_dwordx4 v[164:165], off
	v_lshl_add_u64 v[164:165], v[162:163], 0, s[74:75]
	s_add_i32 m0, s0, 0x4000
	v_lshl_add_u64 v[162:163], v[162:163], 0, s[42:43]
	global_load_lds_dwordx4 v[164:165], off
	s_add_i32 m0, s0, 0x6000
	s_nop 0
	global_load_lds_dwordx4 v[162:163], off
	s_add_i32 m0, s0, 0x8000
	s_nop 0
	global_load_lds_dwordx4 v[160:161], off
	v_lshl_add_u64 v[160:161], v[160:161], 0, s[72:73]
	s_add_i32 m0, s0, 0xa000
	s_nop 0
	global_load_lds_dwordx4 v[160:161], off
	s_waitcnt vmcnt(6)
	s_branch .LBB0_1220

.LBB0_1229:
	s_mul_i32 s54, s52, 0xc000
	v_or_b32_e32 v64, s54, v153
	v_add_u32_e32 v65, v64, v152
	v_add_u32_e32 v64, v64, v154
	ds_read_b128 v[124:127], v65
	ds_read_b128 v[116:119], v65 offset:2048
	ds_read_b128 v[80:83], v64 offset:32768
	ds_read_b128 v[84:87], v64 offset:34816
	ds_read_b128 v[104:107], v65 offset:4096
	ds_read_b128 v[92:95], v65 offset:6144
	ds_read_b128 v[108:111], v64 offset:36864
	ds_read_b128 v[112:115], v64 offset:38912
	v_or_b32_e32 v64, s54, v155
	v_add_u32_e32 v65, v64, v152
	v_add_u32_e32 v68, v64, v154
	ds_read_b128 v[120:123], v65
	ds_read_b128 v[100:103], v65 offset:2048
	ds_read_b128 v[72:75], v68 offset:32768
	ds_read_b128 v[76:79], v68 offset:34816
	ds_read_b128 v[96:99], v65 offset:4096
	ds_read_b128 v[64:67], v65 offset:6144
	ds_read_b128 v[88:91], v68 offset:36864
	ds_read_b128 v[68:71], v68 offset:38912
	s_cmp_lt_u32 s38, 30
	s_cselect_b64 s[0:1], -1, 0
	s_nor_b64 s[14:15], s[8:9], s[0:1]
	s_cbranch_scc1 .LBB0_1231
	v_lshl_add_u64 v[144:145], v[136:137], 0, s[12:13]
	v_lshl_add_u64 v[146:147], v[140:141], 0, s[12:13]
	s_add_i32 s54, s54, 0xffff4000
	v_cndmask_b32_e64 v145, v147, v145, s[0:1]
	v_cndmask_b32_e64 v144, v146, v144, s[0:1]
	v_lshl_add_u64 v[146:147], v[138:139], 0, s[12:13]
	v_lshl_add_u64 v[148:149], v[142:143], 0, s[12:13]
	s_cmp_gt_i32 s52, 0
	v_cndmask_b32_e64 v147, v149, v147, s[0:1]
	v_cndmask_b32_e64 v146, v148, v146, s[0:1]
	s_cselect_b32 s0, s54, 0x18000
	s_add_i32 s0, s19, s0
	s_mov_b32 m0, s0
	v_lshl_add_u64 v[148:149], v[146:147], 0, s[72:73]
	global_load_lds_dwordx4 v[146:147], off
	s_add_i32 m0, s0, 0x2000
	s_nop 0
	global_load_lds_dwordx4 v[148:149], off
	v_lshl_add_u64 v[148:149], v[146:147], 0, s[74:75]
	s_add_i32 m0, s0, 0x4000
	v_lshl_add_u64 v[146:147], v[146:147], 0, s[42:43]
	global_load_lds_dwordx4 v[148:149], off
	s_add_i32 m0, s0, 0x6000
	s_nop 0
	global_load_lds_dwordx4 v[146:147], off
	s_add_i32 m0, s0, 0x8000
	s_nop 0
	global_load_lds_dwordx4 v[144:145], off
	v_lshl_add_u64 v[144:145], v[144:145], 0, s[72:73]
	s_add_i32 m0, s0, 0xa000
	s_nop 0
	global_load_lds_dwordx4 v[144:145], off
.LBB0_1231:
	s_waitcnt lgkmcnt(0)
	v_mfma_f32_16x16x32_bf16 v[60:63], v[80:83], v[124:127], v[60:63]
	s_waitcnt lgkmcnt(0)
	v_mfma_f32_16x16x32_bf16 v[56:59], v[84:87], v[124:127], v[56:59]
	s_barrier
	v_mfma_f32_16x16x32_bf16 v[52:55], v[108:111], v[124:127], v[52:55]
	v_mfma_f32_16x16x32_bf16 v[48:51], v[112:115], v[124:127], v[48:51]
	v_mfma_f32_16x16x32_bf16 v[44:47], v[80:83], v[116:119], v[44:47]
	v_mfma_f32_16x16x32_bf16 v[40:43], v[84:87], v[116:119], v[40:43]
	v_mfma_f32_16x16x32_bf16 v[36:39], v[108:111], v[116:119], v[36:39]
	v_mfma_f32_16x16x32_bf16 v[32:35], v[112:115], v[116:119], v[32:35]
	v_mfma_f32_16x16x32_bf16 v[28:31], v[80:83], v[104:107], v[28:31]
	v_mfma_f32_16x16x32_bf16 v[24:27], v[84:87], v[104:107], v[24:27]
	v_mfma_f32_16x16x32_bf16 v[20:23], v[108:111], v[104:107], v[20:23]
	v_mfma_f32_16x16x32_bf16 v[16:19], v[112:115], v[104:107], v[16:19]
	v_mfma_f32_16x16x32_bf16 v[12:15], v[80:83], v[92:95], v[12:15]
	v_mfma_f32_16x16x32_bf16 v[8:11], v[84:87], v[92:95], v[8:11]
	v_mfma_f32_16x16x32_bf16 v[0:3], v[108:111], v[92:95], v[0:3]
	v_mfma_f32_16x16x32_bf16 v[4:7], v[112:115], v[92:95], v[4:7]
	v_mfma_f32_16x16x32_bf16 v[60:63], v[72:75], v[120:123], v[60:63]
	v_mfma_f32_16x16x32_bf16 v[56:59], v[76:79], v[120:123], v[56:59]
	v_mfma_f32_16x16x32_bf16 v[52:55], v[88:91], v[120:123], v[52:55]
	v_mfma_f32_16x16x32_bf16 v[48:51], v[68:71], v[120:123], v[48:51]
	v_mfma_f32_16x16x32_bf16 v[44:47], v[72:75], v[100:103], v[44:47]
	v_mfma_f32_16x16x32_bf16 v[40:43], v[76:79], v[100:103], v[40:43]
	v_mfma_f32_16x16x32_bf16 v[36:39], v[88:91], v[100:103], v[36:39]
	v_mfma_f32_16x16x32_bf16 v[32:35], v[68:71], v[100:103], v[32:35]
	v_mfma_f32_16x16x32_bf16 v[28:31], v[72:75], v[96:99], v[28:31]
	v_mfma_f32_16x16x32_bf16 v[24:27], v[76:79], v[96:99], v[24:27]
	v_mfma_f32_16x16x32_bf16 v[20:23], v[88:91], v[96:99], v[20:23]
	v_mfma_f32_16x16x32_bf16 v[16:19], v[68:71], v[96:99], v[16:19]
	v_mfma_f32_16x16x32_bf16 v[12:15], v[72:75], v[64:67], v[12:15]
	v_mfma_f32_16x16x32_bf16 v[8:11], v[76:79], v[64:67], v[8:11]
	v_mfma_f32_16x16x32_bf16 v[0:3], v[88:91], v[64:67], v[0:3]
	v_mfma_f32_16x16x32_bf16 v[4:7], v[68:71], v[64:67], v[4:7]
	s_cmp_lg_u64 s[14:15], 0
	s_cbranch_scc1 .Lgk_w5
	s_waitcnt vmcnt(6)
	s_branch .LBB0_1228
